# phases D and F first-tile prologue: row-norm partial-sum loads overlapped with the first LDS staging group instead of two serial round trips
# speedup vs baseline: 1.0027x; 1.0027x over previous
; __device__ __forceinline__ int lane_fresh() { int l; asm volatile("v_mbcnt_lo_u32_b32 %0, -1, 0\n\tv_mbcnt_hi_u32_b32 %0, -1, %0" : "=v"(l)); return l; }
; #define WAIT_V(n) asm volatile("s_waitcnt vmcnt(" #n ")" ::: "memory")
; #define WAIT_L(n) asm volatile("s_waitcnt lgkmcnt(" #n ")" ::: "memory")
; template <int PART  , bool SYNC_FIRST = true>
; __device__ __forceinline__ void kloop_t(const u16* __restrict__ A, int lda, const u16* __restrict__ Bt, int ldb, int K, Acc& acc, const int wv) {
;     ...
;   const int wid = wv, lane = lane_fresh(), ktid = wv * 64 + lane, wr = wid >> 2, wc = wid & 3, fr = lane & 15, fq = lane >> 4;
;   bf16x8 At[4][2], B0[2][2], B1[2][2];
;   const int nt = K / BK;
;   unsigned oA0, oA1, oB0, oB1;
;   { int r_, c_; stage_rc(ktid * 16, r_, c_); oA0 = (unsigned)(r_ * lda + c_) * 2u; oB0 = (unsigned)(r_ * ldb + c_) * 2u;
;     stage_rc(ktid * 16 + 8192, r_, c_); oA1 = (unsigned)(r_ * lda + c_) * 2u; oB1 = (unsigned)(r_ * ldb + c_) * 2u; }
;   if (PART != 2) {
;     if (SYNC_FIRST) { WAIT_V(0); WAIT_L(0); __syncthreads(); }
;     STAGE(SB(0, 0), Bt, ldb, 0, 0); STAGE(SA(0, 0), A, lda, 0, 0);
;     STAGE(SB(0, 1), Bt, ldb, HALF, 0); STAGE(SA(0, 1), A, lda, HALF, 0);
; __device__ __forceinline__ void phaseD(const Params& p, const int wv, const int rep) {
;     ...
;     __syncthreads();
;     {
;       const int tid = wv * 64 + lane_fresh();
;       const int r = tid >> 1, gg = tid & 1;
;       const float* ps = YPS + (size_t)(brow + r) * 32 + gg * 16;
;       f32x4 a = *(const f32x4*)ps + *(const f32x4*)(ps + 4) + *(const f32x4*)(ps + 8) + *(const f32x4*)(ps + 12);
;       rs_l[r * 2 + gg] = rsqrtf((a[0] + a[1] + a[2] + a[3]) * (1.f / 512.f) + EPS);
.LBB0_690:
	s_lshl_b32 s0, s89, 8
	s_and_b32 s90, s0, 0x3f00
	v_readlane_b32 s0, v250, 0
	s_barrier
	v_mbcnt_lo_u32_b32 v0, -1, 0
	v_mbcnt_hi_u32_b32 v0, -1, v0
	v_readlane_b32 s1, v250, 1
	v_add_u32_e32 v18, s0, v0
	v_ashrrev_i32_e32 v2, 1, v18
	v_add_u32_e32 v2, s90, v2
	v_ashrrev_i32_e32 v3, 31, v2
	v_readlane_b32 s0, v251, 4
	v_lshlrev_b64 v[2:3], 7, v[2:3]
	v_readlane_b32 s1, v251, 5
	v_lshlrev_b32_e32 v0, 6, v0
	v_and_b32_e32 v0, 64, v0
	v_lshl_add_u64 v[2:3], s[0:1], 0, v[2:3]
	v_lshl_add_u64 v[14:15], v[2:3], 0, v[0:1]
	global_load_dwordx4 v[200:203], v[14:15], off
	global_load_dwordx4 v[204:207], v[14:15], off offset:16
	global_load_dwordx4 v[208:211], v[14:15], off offset:32
	s_nop 0
	global_load_dwordx4 v[212:215], v[14:15], off offset:48
	s_mov_b32 s5, 0x800000
	v_lshl_add_u32 v216, v18, 2, 16
	v_add_u32_e32 v216, 0x20000, v216
	s_lshl_b32 s0, s89, 2
	s_and_b32 s0, s0, 0x300
	s_lshl_b32 s1, s90, 10
	s_add_u32 s28, s66, s1
	s_addc_u32 s29, s67, 0
	s_lshl_b32 s4, s0, 10
	s_add_u32 s30, s70, s4
	s_addc_u32 s31, s71, 0
	s_add_u32 s6, s30, 0x20000
	s_addc_u32 s7, s31, 0
	s_mov_b32 s33, s19
	v_mbcnt_lo_u32_b32 v0, -1, 0
	v_mbcnt_hi_u32_b32 v0, -1, v0
	s_waitcnt lgkmcnt(0)
	s_waitcnt lgkmcnt(0)
	v_lshl_add_u32 v0, v0, 4, s76
	v_ashrrev_i32_e32 v2, 31, v0
	v_add_u32_e32 v3, 0x2000, v0
	v_add_u32_e32 v4, s94, v0
	v_lshrrev_b32_e32 v2, 22, v2
	v_ashrrev_i32_e32 v6, 31, v3
	v_readfirstlane_b32 s5, v4
	v_add_u32_e32 v4, 0x2000, v4
	v_add_u32_e32 v2, v0, v2
	v_lshrrev_b32_e32 v6, 22, v6
	v_readfirstlane_b32 s9, v4
	v_ashrrev_i32_e32 v2, 10, v2
	v_add_u32_e32 v4, v3, v6
	v_mul_i32_i24_e32 v6, 0x400, v2
	v_ashrrev_i32_e32 v4, 10, v4
	v_sub_u32_e32 v6, v0, v6
	v_mul_i32_i24_e32 v8, 0x400, v4
	v_lshlrev_b32_e32 v9, 3, v4
	v_lshrrev_b32_e32 v10, 4, v6
	v_sub_u32_e32 v3, v3, v8
	v_and_b32_e32 v8, 0x3ffff0, v9
	v_bitop3_b32 v6, v10, v6, 32 bitop3:0x6c
	v_lshrrev_b32_e32 v9, 4, v3
	v_ashrrev_i32_e32 v10, 31, v6
	v_bitop3_b32 v3, v9, v3, 32 bitop3:0x6c
	v_lshrrev_b32_e32 v9, 26, v10
	v_ashrrev_i32_e32 v10, 31, v3
	v_add_u32_e32 v5, 16, v0
	v_add_u32_e32 v9, v6, v9
	v_lshrrev_b32_e32 v10, 26, v10
	v_add_u32_e32 v7, 0x2000, v5
	v_lshrrev_b32_e32 v11, 6, v9
	v_and_b32_e32 v9, 0xc0, v9
	v_add_u32_e32 v10, v3, v10
	v_readfirstlane_b32 s18, v7
	v_lshlrev_b32_e32 v7, 3, v2
	v_lshlrev_b32_e32 v2, 5, v2
	v_sub_u32_e32 v6, v6, v9
	v_lshrrev_b32_e32 v9, 6, v10
	v_and_b32_e32 v10, 0xffc0, v10
	v_and_b32_e32 v2, 32, v2
	v_ashrrev_i16_sdwa v6, v187, sext(v6) dst_sel:DWORD dst_unused:UNUSED_PAD src0_sel:DWORD src1_sel:BYTE_0
	v_sub_u32_e32 v3, v3, v10
	v_add_u32_sdwa v2, v2, sext(v6) dst_sel:DWORD dst_unused:UNUSED_PAD src0_sel:DWORD src1_sel:WORD_0
	v_lshrrev_b16_e32 v6, 7, v3
	v_and_b32_e32 v6, 1, v6
	v_lshlrev_b32_e32 v4, 5, v4
	v_add_u16_e32 v3, v3, v6
	v_and_b32_e32 v7, 0x3ffff0, v7
	v_and_b32_e32 v4, 32, v4
	v_ashrrev_i16_sdwa v3, v187, sext(v3) dst_sel:DWORD dst_unused:UNUSED_PAD src0_sel:DWORD src1_sel:BYTE_0
	v_add_lshl_u32 v7, v11, v7, 10
	v_add_lshl_u32 v8, v9, v8, 10
	v_add_u32_sdwa v3, v4, sext(v3) dst_sel:DWORD dst_unused:UNUSED_PAD src0_sel:DWORD src1_sel:WORD_0
	v_lshl_add_u32 v2, v2, 1, v7
	v_lshl_add_u32 v3, v3, 1, v8
	v_mov_b32_e32 v6, v2
	v_mov_b32_e32 v4, v3
	s_mov_b32 m0, s5
	s_barrier
; __device__ __forceinline__ int lane_fresh() { int l; asm volatile("v_mbcnt_lo_u32_b32 %0, -1, 0\n\tv_mbcnt_hi_u32_b32 %0, -1, %0" : "=v"(l)); return l; }
; #define ACC_ZERO(acc) do { _Pragma("unroll") for (int ai = 0; ai < 2; ++ai) _Pragma("unroll") for (int bj = 0; bj < 2; ++bj) \
;   _Pragma("unroll") for (int m = 0; m < 4; ++m) _Pragma("unroll") for (int n = 0; n < 2; ++n) acc[ai][bj][m][n] = (f32x4){0.f, 0.f, 0.f, 0.f}; } while (0)
; template <int PART  , bool SYNC_FIRST = true>
; __device__ __forceinline__ void kloop_t(const u16* __restrict__ A, int lda, const u16* __restrict__ Bt, int ldb, int K, Acc& acc, const int wv) {
;     ...
;     STAGE(SB(0, 0), Bt, ldb, 0, 0); STAGE(SA(0, 0), A, lda, 0, 0);
;     STAGE(SB(0, 1), Bt, ldb, HALF, 0); STAGE(SA(0, 1), A, lda, HALF, 0);
; __device__ __forceinline__ void phaseD(const Params& p, const int wv, const int rep) {
;     ...
;     {
;       const int tid = wv * 64 + lane_fresh();
;       const int r = tid >> 1, gg = tid & 1;
;       const float* ps = YPS + (size_t)(brow + r) * 32 + gg * 16;
;       f32x4 a = *(const f32x4*)ps + *(const f32x4*)(ps + 4) + *(const f32x4*)(ps + 8) + *(const f32x4*)(ps + 12);
;       rs_l[r * 2 + gg] = rsqrtf((a[0] + a[1] + a[2] + a[3]) * (1.f / 512.f) + EPS);
;     }
;     auto opnd = [&](int br, const u16*& Ap, const u16*& Bp, int& ld) {
;       if (br == 0) { Ap = GM + (size_t)brow * 512; Bp = WGM + (size_t)bcol * 512; ld = 512; }
;       else if (br == 1) { Ap = Y + (size_t)brow * 1024; Bp = WSSD + (size_t)bcol * 1024; ld = 1024; }
;       else if (br == 2) { Ap = Y + (size_t)brow * 1024 + 512; Bp = WSSD + (size_t)bcol * 1024 + 512; ld = 1024; }
;       else { Ap = XA + (size_t)brow * 512; Bp = WXA + (size_t)bcol * 512; ld = 512; }
;     };
;     Acc acc; ACC_ZERO(acc);
;     { const u16 *Ap, *Bp; int ld; opnd(0, Ap, Bp, ld); kloop_t<1, true>(Ap, ld, Bp, ld, 512, acc, wv); }
	v_readfirstlane_b32 s8, v5
	v_mov_b32_e32 v7, v2
	global_load_lds_dwordx4 v6, s[30:31]
	s_mov_b32 m0, s9
	v_mov_b32_e32 v8, v3
	global_load_lds_dwordx4 v4, s[30:31]
	s_mov_b32 m0, s8
	v_add_u32_e32 v0, s95, v0
	v_mov_b32_e32 v9, v2
	global_load_lds_dwordx4 v7, s[28:29]
	s_mov_b32 m0, s18
	v_readfirstlane_b32 s5, v0
	v_add_u32_e32 v0, 0x2000, v0
	v_mov_b32_e32 v10, v3
	global_load_lds_dwordx4 v8, s[28:29]
	s_mov_b32 m0, s5
	v_readfirstlane_b32 s5, v0
	v_add_u32_e32 v0, 0x4000, v5
	global_load_lds_dwordx4 v9, s[6:7]
	s_mov_b32 m0, s5
	v_readfirstlane_b32 s5, v0
	global_load_lds_dwordx4 v10, s[6:7]
	s_add_u32 s6, s28, 0x20000
	v_add_u32_e32 v0, 0x6000, v5
	s_addc_u32 s7, s29, 0
	s_mov_b32 m0, s5
	v_readfirstlane_b32 s5, v0
	v_mov_b32_e32 v0, v1
	global_load_lds_dwordx4 v2, s[6:7]
	s_mov_b32 m0, s5
	s_lshl_b32 s5, s90, 11
	global_load_lds_dwordx4 v3, s[6:7]
	s_waitcnt vmcnt(10)
	v_pk_add_f32 v[200:201], v[200:201], v[204:205]
	v_pk_add_f32 v[202:203], v[202:203], v[206:207]
	s_waitcnt vmcnt(9)
	v_pk_add_f32 v[200:201], v[200:201], v[208:209]
	v_pk_add_f32 v[202:203], v[202:203], v[210:211]
	s_waitcnt vmcnt(8)
	v_pk_add_f32 v[200:201], v[200:201], v[212:213]
	v_pk_add_f32 v[202:203], v[202:203], v[214:215]
	v_add_f32_e32 v200, v200, v201
	v_add_f32_e32 v200, v202, v200
	v_add_f32_e32 v200, v203, v200
	v_fmamk_f32 v200, v200, 0x3b000000, v186
	v_mul_f32_e32 v201, 0x4b800000, v200
	v_cmp_gt_f32_e32 vcc, 0x800000, v200
	s_nop 1
	v_cndmask_b32_e32 v200, v200, v201, vcc
	v_rsq_f32_e32 v200, v200
	s_nop 0
	v_mul_f32_e32 v201, 0x45800000, v200
	v_cndmask_b32_e32 v200, v200, v201, vcc
	ds_write_b32 v216, v200
	s_add_u32 s34, s48, s5
	s_addc_u32 s35, s49, 0
	s_add_u32 s36, s34, 0x400
	s_addc_u32 s37, s35, 0
	s_lshl_b32 s5, s0, 11
	s_add_u32 s38, s72, s5
	s_addc_u32 s39, s73, 0
	s_add_u32 s40, s38, 0x400
	s_addc_u32 s41, s39, 0
	s_add_u32 s42, s68, s1
	s_addc_u32 s43, s69, 0
	s_add_u32 s44, s74, s4
	s_addc_u32 s45, s75, 0
	s_add_i32 s91, s90, s87
	s_lshl_b32 s0, s0, 1
	v_readlane_b32 s1, v250, 29
	s_add_u32 s52, s1, s0
	v_readlane_b32 s1, v250, 31
	v_mov_b32_e32 v2, v1
	v_mov_b32_e32 v3, v1
	s_addc_u32 s53, s1, 0
	v_readlane_b32 s1, v250, 33
	v_mov_b64_e32 v[20:21], v[2:3]
	v_mov_b64_e32 v[24:25], v[2:3]
	v_mov_b64_e32 v[52:53], v[2:3]
	v_mov_b64_e32 v[56:57], v[2:3]
	v_mov_b64_e32 v[68:69], v[2:3]
	v_mov_b64_e32 v[76:77], v[2:3]
	v_mov_b64_e32 v[12:13], v[2:3]
	v_mov_b64_e32 v[16:17], v[2:3]
	v_mov_b64_e32 v[28:29], v[2:3]
	v_mov_b64_e32 v[36:37], v[2:3]
	v_mov_b64_e32 v[60:61], v[2:3]
	v_mov_b64_e32 v[64:65], v[2:3]
	v_mov_b64_e32 v[88:89], v[2:3]
	v_mov_b64_e32 v[96:97], v[2:3]
	v_mov_b64_e32 v[100:101], v[2:3]
	v_mov_b64_e32 v[104:105], v[2:3]
	v_mov_b64_e32 v[128:129], v[2:3]
	v_mov_b64_e32 v[120:121], v[2:3]
	v_mov_b64_e32 v[92:93], v[2:3]
	v_mov_b64_e32 v[84:85], v[2:3]
	v_mov_b64_e32 v[48:49], v[2:3]
	v_mov_b64_e32 v[44:45], v[2:3]
	v_mov_b64_e32 v[112:113], v[2:3]
	v_mov_b64_e32 v[124:125], v[2:3]
	v_mov_b64_e32 v[116:117], v[2:3]
	v_mov_b64_e32 v[108:109], v[2:3]
	v_mov_b64_e32 v[80:81], v[2:3]
	v_mov_b64_e32 v[72:73], v[2:3]
	v_mov_b64_e32 v[40:41], v[2:3]
	v_mov_b64_e32 v[32:33], v[2:3]
	v_mov_b64_e32 v[8:9], v[2:3]
	s_add_u32 s54, s1, s0
	v_readlane_b32 s0, v250, 35
	v_mov_b64_e32 v[18:19], v[0:1]
	v_mov_b64_e32 v[22:23], v[0:1]
	v_mov_b64_e32 v[50:51], v[0:1]
	v_mov_b64_e32 v[54:55], v[0:1]
	v_mov_b64_e32 v[66:67], v[0:1]
	v_mov_b64_e32 v[74:75], v[0:1]
	v_mov_b64_e32 v[10:11], v[0:1]
	v_mov_b64_e32 v[14:15], v[0:1]
	v_mov_b64_e32 v[26:27], v[0:1]
	v_mov_b64_e32 v[34:35], v[0:1]
	v_mov_b64_e32 v[58:59], v[0:1]
	v_mov_b64_e32 v[62:63], v[0:1]
	v_mov_b64_e32 v[86:87], v[0:1]
	v_mov_b64_e32 v[94:95], v[0:1]
	v_mov_b64_e32 v[98:99], v[0:1]
	v_mov_b64_e32 v[102:103], v[0:1]
	v_mov_b64_e32 v[126:127], v[0:1]
	v_mov_b64_e32 v[118:119], v[0:1]
	v_mov_b64_e32 v[90:91], v[0:1]
	v_mov_b64_e32 v[82:83], v[0:1]
	v_mov_b64_e32 v[46:47], v[0:1]
	v_mov_b64_e32 v[42:43], v[0:1]
	v_mov_b64_e32 v[110:111], v[0:1]
	v_mov_b64_e32 v[122:123], v[0:1]
	v_mov_b64_e32 v[114:115], v[0:1]
	v_mov_b64_e32 v[106:107], v[0:1]
	v_mov_b64_e32 v[78:79], v[0:1]
	v_mov_b64_e32 v[70:71], v[0:1]
	v_mov_b64_e32 v[38:39], v[0:1]
	v_mov_b64_e32 v[30:31], v[0:1]
	v_mov_b64_e32 v[6:7], v[0:1]
	v_mov_b64_e32 v[4:5], v[2:3]
	s_addc_u32 s55, s0, 0
	v_mov_b64_e32 v[2:3], v[0:1]
	s_branch .LBB0_692

; __device__ __forceinline__ int lane_fresh() { int l; asm volatile("v_mbcnt_lo_u32_b32 %0, -1, 0\n\tv_mbcnt_hi_u32_b32 %0, -1, %0" : "=v"(l)); return l; }
; #define WAIT_V(n) asm volatile("s_waitcnt vmcnt(" #n ")" ::: "memory")
; #define WAIT_L(n) asm volatile("s_waitcnt lgkmcnt(" #n ")" ::: "memory")
; template <int PART  , bool SYNC_FIRST = true>
; __device__ __forceinline__ void kloop_t(const u16* __restrict__ A, int lda, const u16* __restrict__ Bt, int ldb, int K, Acc& acc, const int wv) {
;     ...
;   const int wid = wv, lane = lane_fresh(), ktid = wv * 64 + lane, wr = wid >> 2, wc = wid & 3, fr = lane & 15, fq = lane >> 4;
;   bf16x8 At[4][2], B0[2][2], B1[2][2];
;   const int nt = K / BK;
;   unsigned oA0, oA1, oB0, oB1;
;   { int r_, c_; stage_rc(ktid * 16, r_, c_); oA0 = (unsigned)(r_ * lda + c_) * 2u; oB0 = (unsigned)(r_ * ldb + c_) * 2u;
;     stage_rc(ktid * 16 + 8192, r_, c_); oA1 = (unsigned)(r_ * lda + c_) * 2u; oB1 = (unsigned)(r_ * ldb + c_) * 2u; }
;   if (PART != 2) {
;     if (SYNC_FIRST) { WAIT_V(0); WAIT_L(0); __syncthreads(); }
;     STAGE(SB(0, 0), Bt, ldb, 0, 0); STAGE(SA(0, 0), A, lda, 0, 0);
;     STAGE(SB(0, 1), Bt, ldb, HALF, 0); STAGE(SA(0, 1), A, lda, HALF, 0);
; __device__ __forceinline__ void phaseF(const Params& p, const int wv, const int rep) {
;     ...
;     auto fill_rs = [&](int t, int buf) {
;       const int tid = wv * 64 + lane_fresh();
;       if (tid < 256) {
;         const float* ps = PS + (size_t)((t & 63) * 256 + tid) * 16;
;         f32x4 a = *(const f32x4*)ps + *(const f32x4*)(ps + 4) + *(const f32x4*)(ps + 8) + *(const f32x4*)(ps + 12);
;         rs_l[buf * 256 + tid] = rsqrtf((a[0] + a[1] + a[2] + a[3]) * (1.f / 1024.f) + EPS);
;       }
;     };
;     int t_ = blockIdx.x, it = 0;
;     const int tend = 1024 * rep;
;     Acc acc;
;     if (t_ < tend) {
;       const int t = t_ & 1023;
;       fill_rs(t, 0);
;       kloop_t<1, true>(H2B + (size_t)((t & 63) * 256) * 1024, 1024, WUP + (size_t)((t >> 6) * 256) * 1024, 1024, 1024, acc, wv);
.LBB0_1060:
	s_add_u32 s33, s50, 0x1600000
	s_addc_u32 s44, s51, 0
	s_add_u32 s0, s50, 0x3126000
	s_waitcnt lgkmcnt(0)
	s_barrier
	s_addc_u32 s1, s51, 0
	s_lshl_b32 s45, s58, 10
	v_readlane_b32 s4, v251, 0
	s_cmp_ge_i32 s4, s45
	s_cbranch_scc1 .LBB0_1075
	v_mbcnt_lo_u32_b32 v0, -1, 0
	v_mbcnt_hi_u32_b32 v0, -1, v0
	v_readlane_b32 s4, v251, 0
	v_add_u32_e32 v0, s88, v0
	s_movk_i32 s52, 0x100
	s_and_b32 s12, s4, 0x3ff
	v_cmp_gt_i32_e32 vcc, s52, v0
	s_and_saveexec_b64 s[4:5], vcc
	s_cbranch_execz .LBB0_1063
	s_lshl_b32 s13, s12, 8
	s_and_b32 s13, s13, 0x3f00
	v_add_u32_e32 v2, s13, v0
	v_ashrrev_i32_e32 v3, 31, v2
	v_lshlrev_b64 v[2:3], 6, v[2:3]
	v_lshl_add_u64 v[18:19], s[0:1], 0, v[2:3]
	global_load_dwordx4 v[200:203], v[18:19], off
	global_load_dwordx4 v[204:207], v[18:19], off offset:16
	global_load_dwordx4 v[208:211], v[18:19], off offset:32
	global_load_dwordx4 v[212:215], v[18:19], off offset:48
.LBB0_1063:
	s_or_b64 exec, exec, s[4:5]
	v_readlane_b32 s75, v251, 0
	s_lshl_b32 s4, s75, 19
	s_and_b32 s4, s4, 0x1f80000
	s_add_u32 s4, s8, s4
	s_addc_u32 s5, s9, 0
	s_lshl_b32 s12, s12, 13
	s_and_b32 s12, s12, 0x780000
	s_add_u32 s12, s33, s12
	s_addc_u32 s13, s44, 0
	v_mbcnt_lo_u32_b32 v0, -1, 0
	v_mbcnt_hi_u32_b32 v0, -1, v0
	s_lshl_b32 s53, s90, 10
	v_lshl_add_u32 v0, v0, 4, s53
	v_ashrrev_i32_e32 v1, 31, v0
	v_lshrrev_b32_e32 v1, 22, v1
	v_add_u32_e32 v1, v0, v1
	v_ashrrev_i32_e32 v1, 10, v1
	v_mul_i32_i24_e32 v2, 0x400, v1
	v_sub_u32_e32 v2, v0, v2
	v_lshrrev_b32_e32 v3, 4, v2
	v_bitop3_b32 v2, v3, v2, 32 bitop3:0x6c
	v_ashrrev_i32_e32 v4, 31, v2
	v_lshrrev_b32_e32 v4, 26, v4
	v_add_u32_e32 v4, v2, v4
	v_lshrrev_b32_e32 v5, 6, v4
	v_and_b32_e32 v4, 0xc0, v4
	v_lshlrev_b32_e32 v3, 3, v1
	v_lshlrev_b32_e32 v1, 5, v1
	v_sub_u32_e32 v2, v2, v4
	v_mov_b32_e32 v132, 1
	v_and_b32_e32 v3, 0x1ffff0, v3
	v_and_b32_e32 v1, 32, v1
	v_ashrrev_i16_sdwa v2, v132, sext(v2) dst_sel:DWORD dst_unused:UNUSED_PAD src0_sel:DWORD src1_sel:BYTE_0
	v_add_u32_sdwa v1, v1, sext(v2) dst_sel:DWORD dst_unused:UNUSED_PAD src0_sel:DWORD src1_sel:WORD_0
	v_add_lshl_u32 v2, v5, v3, 11
	v_lshl_add_u32 v1, v1, 1, v2
	v_add_u32_e32 v2, 0x2000, v0
	v_ashrrev_i32_e32 v3, 31, v2
	v_lshrrev_b32_e32 v3, 22, v3
	v_add_u32_e32 v3, v2, v3
	v_ashrrev_i32_e32 v3, 10, v3
	v_mul_i32_i24_e32 v4, 0x400, v3
	v_sub_u32_e32 v2, v2, v4
	v_lshrrev_b32_e32 v4, 4, v2
	v_bitop3_b32 v2, v4, v2, 32 bitop3:0x6c
	v_ashrrev_i32_e32 v5, 31, v2
	v_lshrrev_b32_e32 v5, 26, v5
	v_add_u32_e32 v5, v2, v5
	v_lshrrev_b32_e32 v6, 6, v5
	v_and_b32_e32 v5, 0xffc0, v5
	v_sub_u32_e32 v2, v2, v5
	v_lshrrev_b16_e32 v5, 7, v2
	v_and_b32_e32 v5, 1, v5
	v_lshlrev_b32_e32 v4, 3, v3
	v_lshlrev_b32_e32 v3, 5, v3
	v_add_u16_e32 v2, v2, v5
	v_and_b32_e32 v4, 0x1ffff0, v4
	v_and_b32_e32 v3, 32, v3
	v_ashrrev_i16_sdwa v2, v132, sext(v2) dst_sel:DWORD dst_unused:UNUSED_PAD src0_sel:DWORD src1_sel:BYTE_0
	v_add_u32_sdwa v2, v3, sext(v2) dst_sel:DWORD dst_unused:UNUSED_PAD src0_sel:DWORD src1_sel:WORD_0
	v_add_lshl_u32 v3, v6, v4, 11
	s_add_i32 s54, 16, 0x10000
	v_lshl_add_u32 v2, v2, 1, v3
	v_add_u32_e32 v5, s54, v0
	v_mov_b32_e32 v3, v1
	v_mov_b32_e32 v4, v2
	v_readfirstlane_b32 s14, v5
	s_waitcnt lgkmcnt(0)
	s_waitcnt lgkmcnt(0)
	s_barrier
	s_mov_b32 m0, s14
	v_readlane_b32 s16, v251, 1
	global_load_lds_dwordx4 v3, s[12:13]
	v_add_u32_e32 v3, 0x2000, v5
	v_add_u32_e32 v5, 16, v0
	v_readfirstlane_b32 s14, v3
	s_mov_b32 m0, s14
	v_mov_b32_e32 v3, v1
	global_load_lds_dwordx4 v4, s[12:13]
	v_mov_b32_e32 v4, v2
	v_readfirstlane_b32 s14, v5
	s_mov_b32 m0, s14
	s_add_u32 s12, s12, 0x40000
	global_load_lds_dwordx4 v3, s[4:5]
	v_add_u32_e32 v3, 0x2000, v5
	s_addc_u32 s13, s13, 0
	s_add_i32 s55, 16, 0x14000
	v_readfirstlane_b32 s14, v3
	v_add_u32_e32 v0, s55, v0
	s_mov_b32 m0, s14
	v_readfirstlane_b32 s14, v0
	v_add_u32_e32 v0, 0x2000, v0
	global_load_lds_dwordx4 v4, s[4:5]
	v_mov_b32_e32 v3, v1
	v_mov_b32_e32 v4, v2
	s_mov_b32 m0, s14
	v_readfirstlane_b32 s14, v0
	v_add_u32_e32 v0, 0x4000, v5
	global_load_lds_dwordx4 v3, s[12:13]
	s_mov_b32 m0, s14
	s_add_u32 s4, s4, 0x40000
	global_load_lds_dwordx4 v4, s[12:13]
	v_readfirstlane_b32 s12, v0
	v_add_u32_e32 v0, 0x6000, v5
	s_addc_u32 s5, s5, 0
	s_mov_b32 m0, s12
	v_readfirstlane_b32 s12, v0
	s_mov_b32 s13, 0
	global_load_lds_dwordx4 v1, s[4:5]
	s_mov_b32 m0, s12
	s_lshr_b32 s12, s91, 8
	global_load_lds_dwordx4 v2, s[4:5]
	s_cmp_eq_u32 s12, 1
	s_cselect_b64 s[4:5], -1, 0
	s_lshl_b32 s14, s90, 2
	s_lshl_b32 s57, s12, 6
	s_and_b32 s56, s14, 12
	s_or_b32 s60, s57, 16
	s_or_b32 s62, s57, 32
	s_or_b32 s64, s57, 48
	s_or_b32 s58, s56, 2
	s_lshl_b32 s59, s12, 3
	s_lshr_b32 s61, s60, 3
	s_lshr_b32 s63, s62, 3
	s_lshr_b32 s65, s64, 3
	s_cmpk_lt_u32 s91, 0x100
	s_cselect_b64 s[14:15], -1, 0
	s_lshl_b32 s12, s90, 4
	s_and_b32 s66, s12, 0x3fffffc0
	s_lshl_b32 s12, s90, 5
	s_and_b32 s12, s12, 0x60
	v_cndmask_b32_e64 v0, 0, 1, s[4:5]
	s_lshl_b32 s67, s75, 8
	s_lshl_b32 s68, s16, 8
	s_lshl_b32 s69, s75, 2
	s_lshl_b32 s70, s16, 2
	v_cmp_ne_u32_e64 s[4:5], 1, v0
	v_mov_b32_e32 v129, 0
	s_mov_b64 s[16:17], 0x80
	s_add_i32 s71, 16, 0x18000
	s_add_i32 s72, 16, 0x1c000
	s_movk_i32 s73, 0x3c0
	s_mov_b64 s[18:19], 0xf3ee080
	s_mov_b64 s[20:21], 0x1600100
	s_mov_b64 s[22:23], 0xf3ae100
	s_mov_b64 s[24:25], 0x1640100
	s_mov_b64 s[26:27], 0xf3ee100
	s_mov_b64 s[28:29], 0x1600180
	s_mov_b64 s[30:31], 0xf3ae180
	s_mov_b64 s[34:35], 0x1640180
	v_mov_b32_e32 v133, 0x358637bd
	s_mov_b32 s74, 0x800000
	s_lshl_b32 s12, s12, 1
	s_mov_b32 s76, s13
	v_mbcnt_lo_u32_b32 v220, -1, 0
	v_mbcnt_hi_u32_b32 v220, -1, v220
	v_add_u32_e32 v220, s88, v220
	v_cmp_gt_i32_e32 vcc, s52, v220
	s_and_saveexec_b64 s[98:99], vcc
	s_cbranch_execz .Lfpro_skip
	v_lshl_add_u32 v220, v220, 2, 16
	v_add_u32_e32 v220, 0x20000, v220
	v_mov_b32_e32 v221, 0x358637bd
	s_waitcnt vmcnt(10)
	v_pk_add_f32 v[200:201], v[200:201], v[204:205]
	v_pk_add_f32 v[202:203], v[202:203], v[206:207]
	s_waitcnt vmcnt(9)
	v_pk_add_f32 v[200:201], v[200:201], v[208:209]
	v_pk_add_f32 v[202:203], v[202:203], v[210:211]
	s_waitcnt vmcnt(8)
	v_pk_add_f32 v[200:201], v[200:201], v[212:213]
	v_pk_add_f32 v[202:203], v[202:203], v[214:215]
	v_add_f32_e32 v200, v200, v201
	v_add_f32_e32 v200, v202, v200
	v_add_f32_e32 v200, v203, v200
	v_fmac_f32_e32 v221, 0x3a800000, v200
	v_mul_f32_e32 v200, 0x4b800000, v221
	v_cmp_gt_f32_e32 vcc, s74, v221
	s_nop 1
	v_cndmask_b32_e32 v221, v221, v200, vcc
	v_rsq_f32_e32 v221, v221
	s_nop 0
	v_mul_f32_e32 v200, 0x45800000, v221
	v_cndmask_b32_e32 v221, v221, v200, vcc
	ds_write_b32 v220, v221
.Lfpro_skip:
	s_or_b64 exec, exec, s[98:99]
	s_branch .LBB0_1066

; __global__ void __launch_bounds__(NTHREADS) fwd_megakernel(Params p) {
;   cg::grid_group grid = cg::this_grid();
;   const int wv = __builtin_amdgcn_readfirstlane(threadIdx.x >> 6);
	.amdhsa_kernel _Z14fwd_megakernel6Params
		.amdhsa_group_segment_fixed_size 16
		.amdhsa_private_segment_fixed_size 0
		.amdhsa_kernarg_size 512
		.amdhsa_user_sgpr_count 2
		.amdhsa_user_sgpr_dispatch_ptr 0
		.amdhsa_user_sgpr_queue_ptr 0
		.amdhsa_user_sgpr_kernarg_segment_ptr 1
		.amdhsa_user_sgpr_dispatch_id 0
		.amdhsa_user_sgpr_kernarg_preload_length 0
		.amdhsa_user_sgpr_kernarg_preload_offset 0
		.amdhsa_user_sgpr_private_segment_size 0
		.amdhsa_uses_dynamic_stack 0
		.amdhsa_enable_private_segment 0
		.amdhsa_system_sgpr_workgroup_id_x 1
		.amdhsa_system_sgpr_workgroup_id_y 0
		.amdhsa_system_sgpr_workgroup_id_z 0
		.amdhsa_system_sgpr_workgroup_info 0
		.amdhsa_system_vgpr_workitem_id 2
		.amdhsa_next_free_vgpr 252
		.amdhsa_next_free_sgpr 100
		.amdhsa_accum_offset 252
		.amdhsa_reserve_vcc 1
		.amdhsa_float_round_mode_32 0
		.amdhsa_float_round_mode_16_64 0
		.amdhsa_float_denorm_mode_32 3
		.amdhsa_float_denorm_mode_16_64 3
		.amdhsa_dx10_clamp 1
		.amdhsa_ieee_mode 1
		.amdhsa_fp16_overflow 0
		.amdhsa_tg_split 0
		.amdhsa_exception_fp_ieee_invalid_op 0
		.amdhsa_exception_fp_denorm_src 0
		.amdhsa_exception_fp_ieee_div_zero 0
		.amdhsa_exception_fp_ieee_overflow 0
		.amdhsa_exception_fp_ieee_underflow 0
		.amdhsa_exception_fp_ieee_inexact 0
		.amdhsa_exception_int_div_zero 0
	.end_amdhsa_kernel

; __global__ void __launch_bounds__(NTHREADS) fwd_megakernel(Params p) {
amdhsa.kernels:
  - .agpr_count:     0
    .args:
      - .offset:         0
        .size:           256
        .value_kind:     by_value
      - .offset:         256
        .size:           4
        .value_kind:     hidden_block_count_x
      - .offset:         260
        .size:           4
        .value_kind:     hidden_block_count_y
      - .offset:         264
        .size:           4
        .value_kind:     hidden_block_count_z
      - .offset:         268
        .size:           2
        .value_kind:     hidden_group_size_x
      - .offset:         270
        .size:           2
        .value_kind:     hidden_group_size_y
      - .offset:         272
        .size:           2
        .value_kind:     hidden_group_size_z
      - .offset:         274
        .size:           2
        .value_kind:     hidden_remainder_x
      - .offset:         276
        .size:           2
        .value_kind:     hidden_remainder_y
      - .offset:         278
        .size:           2
        .value_kind:     hidden_remainder_z
      - .offset:         296
        .size:           8
        .value_kind:     hidden_global_offset_x
      - .offset:         304
        .size:           8
        .value_kind:     hidden_global_offset_y
      - .offset:         312
        .size:           8
        .value_kind:     hidden_global_offset_z
      - .offset:         320
        .size:           2
        .value_kind:     hidden_grid_dims
      - .offset:         344
        .size:           8
        .value_kind:     hidden_multigrid_sync_arg
      - .offset:         376
        .size:           4
        .value_kind:     hidden_dynamic_lds_size
    .group_segment_fixed_size: 16
    .kernarg_segment_align: 8
    .kernarg_segment_size: 512
    .language:       OpenCL C
    .language_version:
      - 2
      - 0
    .max_flat_workgroup_size: 512
    .name:           _Z14fwd_megakernel6Params
    .private_segment_fixed_size: 0
    .sgpr_count:     106
    .sgpr_spill_count: 126
    .symbol:         _Z14fwd_megakernel6Params.kd
    .uniform_work_group_size: 1
    .uses_dynamic_stack: false
    .vgpr_count:     252
    .vgpr_spill_count: 0
    .wavefront_size: 64
